# v52 plus non-temporal hint on the final LayerNorm phase's last-use loads and write-once output stores
# speedup vs baseline: 1.0016x; 1.0016x over previous
.LBB0_1634:
	s_load_dwordx8 s[40:47], s[4:5], 0xb0
	v_lshlrev_b32_e32 v56, 3, v0
	v_add_u32_e32 v24, 0x204, v56
	v_ashrrev_i32_e32 v57, 31, v56
	v_ashrrev_i32_e32 v25, 31, v24
	s_waitcnt lgkmcnt(0)
	s_add_u32 s4, s40, 0x3000
	s_addc_u32 s5, s41, 0
	s_add_u32 s8, s42, 0x3000
	v_lshlrev_b64 v[8:9], 2, v[56:57]
	v_lshlrev_b64 v[28:29], 2, v[24:25]
	s_addc_u32 s9, s43, 0
	v_lshl_add_u64 v[16:17], s[4:5], 0, v[8:9]
	v_lshl_add_u64 v[24:25], s[4:5], 0, v[28:29]
	s_lshl_b32 s4, s6, 3
	v_mov_b32_e32 v32, s46
	v_mov_b32_e32 v33, s47
	s_add_i32 s1, s0, s4
	v_lshl_add_u64 v[20:21], s[8:9], 0, v[8:9]
	v_lshl_add_u64 v[28:29], s[8:9], 0, v[28:29]
	v_lshl_add_u64 v[32:33], v[56:57], 1, v[32:33]
	s_mov_b64 s[8:9], 0x15f10000
	s_cmp_lt_i32 s1, 0x10200
	v_lshl_add_u64 v[58:59], v[32:33], 0, s[8:9]
	s_cselect_b32 s8, s1, s0
	s_ashr_i32 s9, s8, 31
	s_lshl_b64 s[8:9], s[8:9], 11
	s_ashr_i32 s1, s0, 31
	global_load_dwordx4 v[0:3], v[16:17], off offset:16
	global_load_dwordx4 v[4:7], v[16:17], off
	global_load_dwordx4 v[8:11], v[20:21], off offset:16
	global_load_dwordx4 v[12:15], v[20:21], off
	s_nop 0
	global_load_dwordx4 v[16:19], v[16:17], off offset:2048
	s_nop 0
	global_load_dwordx4 v[20:23], v[20:21], off offset:2048
	v_lshl_add_u64 v[36:37], v[58:59], 0, s[8:9]
	s_lshl_b64 s[8:9], s[0:1], 11
	v_lshl_add_u64 v[40:41], v[58:59], 0, s[8:9]
	global_load_dwordx4 v[24:27], v[24:25], off nt
	s_lshl_b32 s1, s6, 4
	global_load_dwordx4 v[28:31], v[28:29], off nt
	s_nop 0
	global_load_dwordx4 v[32:35], v[36:37], off offset:1024 nt
	s_nop 0
	global_load_dwordx4 v[36:39], v[36:37], off nt
	s_nop 0
	global_load_dwordx4 v[52:55], v[40:41], off offset:1024 nt
	global_load_dwordx4 v[48:51], v[40:41], off nt
.LBB0_1635:
	s_add_i32 s5, s0, s1
	s_waitcnt vmcnt(0)
	v_lshlrev_b32_e32 v69, 16, v49
	v_lshlrev_b32_e32 v68, 16, v48
	v_and_b32_e32 v49, 0xffff0000, v49
	v_and_b32_e32 v48, 0xffff0000, v48
	s_cmp_lt_i32 s5, 0x10200
	v_pk_add_f32 v[70:71], v[68:69], v[48:49]
	v_lshlrev_b32_e32 v64, 16, v53
	v_and_b32_e32 v65, 0xffff0000, v53
	s_cselect_b32 s6, s5, s0
	v_add_f32_e32 v53, v70, v71
	v_lshlrev_b32_e32 v71, 16, v51
	v_lshlrev_b32_e32 v70, 16, v50
	v_and_b32_e32 v51, 0xffff0000, v51
	v_and_b32_e32 v50, 0xffff0000, v50
	s_ashr_i32 s7, s6, 31
	v_pk_add_f32 v[72:73], v[70:71], v[50:51]
	v_mov_b64_e32 v[46:47], v[34:35]
	v_lshlrev_b32_e32 v62, 16, v52
	v_and_b32_e32 v63, 0xffff0000, v52
	s_lshl_b64 s[6:7], s[6:7], 11
	v_pk_add_f32 v[72:73], v[72:73], v[72:73] op_sel_hi:[0,1]
	v_mov_b64_e32 v[42:43], v[38:39]
	v_mov_b64_e32 v[44:45], v[32:33]
	v_lshlrev_b32_e32 v60, 16, v54
	v_and_b32_e32 v66, 0xffff0000, v54
	v_lshlrev_b32_e32 v52, 16, v55
	v_and_b32_e32 v54, 0xffff0000, v55
	v_lshl_add_u64 v[32:33], v[58:59], 0, s[6:7]
	v_add_f32_e32 v55, 0, v53
	v_add_f32_e32 v61, v62, v63
	v_add_f32_e32 v67, v64, v65
	v_mov_b32_e32 v53, v73
	v_mov_b64_e32 v[40:41], v[36:37]
	global_load_dwordx4 v[36:39], v[32:33], off nt
	s_nop 0
	global_load_dwordx4 v[32:35], v[32:33], off offset:1024 nt
	v_pk_add_f32 v[74:75], v[60:61], v[66:67]
	v_pk_add_f32 v[72:73], v[52:53], v[54:55]
	v_mbcnt_lo_u32_b32 v55, -1, 0
	v_mbcnt_hi_u32_b32 v55, -1, v55
	s_nop 0
	v_pk_add_f32 v[72:73], v[74:75], v[72:73]
	v_lshlrev_b32_e32 v55, 2, v55
	v_add_f32_e32 v53, v72, v73
	v_xor_b32_e32 v61, 4, v55
	ds_bpermute_b32 v61, v61, v53
	s_waitcnt lgkmcnt(0)
	v_add_f32_e32 v53, v53, v61
	v_xor_b32_e32 v61, 8, v55
	ds_bpermute_b32 v61, v61, v53
	s_waitcnt lgkmcnt(0)
	v_add_f32_e32 v53, v53, v61
	v_xor_b32_e32 v61, 16, v55
	ds_bpermute_b32 v61, v61, v53
	s_waitcnt lgkmcnt(0)
	v_add_f32_e32 v53, v53, v61
	v_xor_b32_e32 v61, 32, v55
	ds_bpermute_b32 v61, v61, v53
	s_waitcnt lgkmcnt(0)
	v_add_f32_e32 v53, v53, v61
	v_xor_b32_e32 v61, 64, v55
	ds_bpermute_b32 v61, v61, v53
	v_xor_b32_e32 v55, 0x80, v55
	s_waitcnt lgkmcnt(0)
	v_add_f32_e32 v53, v53, v61
	ds_bpermute_b32 v55, v55, v53
	s_waitcnt lgkmcnt(0)
	v_add_f32_e32 v53, v53, v55
	v_fmac_f32_e32 v48, 0xba800000, v53
	v_fmac_f32_e32 v49, 0xba800000, v53
	v_fmac_f32_e32 v69, 0xba800000, v53
	v_fmac_f32_e32 v68, 0xba800000, v53
	v_mov_b32_e32 v72, v69
	v_mov_b32_e32 v73, v49
	v_mov_b32_e32 v69, v48
	v_pk_mul_f32 v[74:75], v[72:73], v[72:73]
	v_pk_mul_f32 v[48:49], v[68:69], v[68:69]
	v_fmac_f32_e32 v50, 0xba800000, v53
	v_pk_mov_b32 v[76:77], v[48:49], v[74:75] op_sel:[1,0]
	v_mov_b32_e32 v49, v75
	v_fmac_f32_e32 v51, 0xba800000, v53
	v_fmac_f32_e32 v71, 0xba800000, v53
	v_pk_add_f32 v[48:49], v[76:77], v[48:49]
	v_fmac_f32_e32 v70, 0xba800000, v53
	v_mov_b32_e32 v74, v71
	v_mov_b32_e32 v75, v51
	v_mov_b32_e32 v71, v50
	v_pk_add_f32 v[48:49], v[48:49], v[48:49] op_sel_hi:[0,1]
	v_pk_mul_f32 v[76:77], v[74:75], v[74:75]
	v_pk_mul_f32 v[50:51], v[70:71], v[70:71]
	v_fmac_f32_e32 v62, 0xba800000, v53
	v_pk_mov_b32 v[78:79], v[50:51], v[76:77] op_sel:[1,0]
	v_mov_b32_e32 v51, v77
	v_fmac_f32_e32 v63, 0xba800000, v53
	v_fmac_f32_e32 v64, 0xba800000, v53
	v_mul_f32_e32 v48, v62, v62
	v_pk_add_f32 v[50:51], v[78:79], v[50:51]
	v_fmac_f32_e32 v65, 0xba800000, v53
	v_pk_fma_f32 v[76:77], v[62:63], v[62:63], v[48:49] op_sel_hi:[1,1,0]
	v_mul_f32_e32 v48, v64, v64
	v_pk_add_f32 v[50:51], v[50:51], v[50:51] op_sel_hi:[0,1]
	v_pk_fma_f32 v[78:79], v[64:65], v[64:65], v[48:49] op_sel_hi:[1,1,0]
	v_fmac_f32_e32 v54, 0xba800000, v53
	v_fmac_f32_e32 v52, 0xba800000, v53
	v_fmac_f32_e32 v66, 0xba800000, v53
	v_fmac_f32_e32 v60, 0xba800000, v53
	v_mul_f32_e32 v76, v60, v60
	v_mul_f32_e32 v78, v66, v66
	v_mul_f32_e32 v48, v52, v52
	v_mul_f32_e32 v50, v54, v54
	v_pk_add_f32 v[76:77], v[76:77], v[78:79]
	v_pk_add_f32 v[48:49], v[48:49], v[50:51]
	v_mov_b32_e32 v61, v66
	v_pk_add_f32 v[48:49], v[76:77], v[48:49]
	s_nop 0
	v_add_f32_e32 v48, v48, v49
	v_mbcnt_lo_u32_b32 v49, -1, 0
	v_mbcnt_hi_u32_b32 v49, -1, v49
	s_nop 0
	v_lshlrev_b32_e32 v49, 2, v49
	v_xor_b32_e32 v50, 4, v49
	ds_bpermute_b32 v50, v50, v48
	s_waitcnt lgkmcnt(0)
	v_add_f32_e32 v48, v48, v50
	v_xor_b32_e32 v50, 8, v49
	ds_bpermute_b32 v50, v50, v48
	s_waitcnt lgkmcnt(0)
	v_add_f32_e32 v48, v48, v50
	v_xor_b32_e32 v50, 16, v49
	ds_bpermute_b32 v50, v50, v48
	s_waitcnt lgkmcnt(0)
	v_add_f32_e32 v48, v48, v50
	v_xor_b32_e32 v50, 32, v49
	ds_bpermute_b32 v50, v50, v48
	s_waitcnt lgkmcnt(0)
	v_add_f32_e32 v48, v48, v50
	v_xor_b32_e32 v50, 64, v49
	ds_bpermute_b32 v50, v50, v48
	v_xor_b32_e32 v49, 0x80, v49
	s_waitcnt lgkmcnt(0)
	v_add_f32_e32 v48, v48, v50
	ds_bpermute_b32 v49, v49, v48
	s_waitcnt lgkmcnt(0)
	v_add_f32_e32 v48, v48, v49
	v_mov_b32_e32 v49, 0x3727c5ac
	v_fmamk_f32 v48, v48, 0x3a800000, v49
	v_cmp_gt_f32_e32 vcc, s97, v48
	v_mul_f32_e32 v49, 0x4f800000, v48
	s_nop 0
	v_cndmask_b32_e32 v48, v48, v49, vcc
	v_sqrt_f32_e32 v49, v48
	s_nop 0
	v_add_u32_e32 v50, -1, v49
	v_fma_f32 v51, -v50, v49, v48
	v_cmp_ge_f32_e64 s[38:39], 0, v51
	v_add_u32_e32 v51, 1, v49
	s_nop 0
	v_cndmask_b32_e64 v50, v49, v50, s[38:39]
	v_fma_f32 v49, -v51, v49, v48
	v_cmp_lt_f32_e64 s[38:39], 0, v49
	s_nop 1
	v_cndmask_b32_e64 v49, v50, v51, s[38:39]
	v_mul_f32_e32 v50, 0x37800000, v49
	v_cndmask_b32_e32 v49, v49, v50, vcc
	v_cmp_class_f32_e32 vcc, v48, v248
	s_nop 1
	v_cndmask_b32_e32 v48, v49, v48, vcc
	v_div_scale_f32 v49, s[6:7], v48, v48, 1.0
	v_rcp_f32_e32 v50, v49
	s_add_i32 s6, s0, 0xffff0000
	s_ashr_i32 s7, s0, 31
	s_cmp_lt_i32 s0, 0x10000
	v_fma_f32 v51, -v49, v50, 1.0
	v_fmac_f32_e32 v50, v51, v50
	v_div_scale_f32 v51, vcc, 1.0, v48, 1.0
	v_mul_f32_e32 v53, v51, v50
	v_fma_f32 v55, -v49, v53, v51
	v_fmac_f32_e32 v53, v55, v50
	s_cselect_b32 s6, s0, s6
	s_cselect_b32 s0, 0, 0x10000000
	v_fma_f32 v49, -v49, v53, v51
	s_cselect_b32 s7, s7, 0
	s_add_u32 s0, s44, s0
	v_div_fmas_f32 v49, v49, v50, v53
	s_addc_u32 s8, s45, 0
	s_lshl_b64 s[6:7], s[6:7], 12
	v_div_fixup_f32 v76, v49, v48, 1.0
	s_add_u32 s6, s0, s6
	s_addc_u32 s7, s8, s7
	v_pk_mul_f32 v[48:49], v[68:69], v[76:77] op_sel_hi:[1,0]
	v_pk_mul_f32 v[50:51], v[72:73], v[76:77] op_sel_hi:[1,0]
	v_pk_fma_f32 v[48:49], v[4:5], v[48:49], v[12:13]
	v_pk_fma_f32 v[50:51], v[6:7], v[50:51], v[14:15]
	v_pk_mul_f32 v[68:69], v[70:71], v[76:77] op_sel_hi:[1,0]
	v_pk_mul_f32 v[70:71], v[74:75], v[76:77] op_sel_hi:[1,0]
	v_lshl_add_u64 v[72:73], v[56:57], 2, s[6:7]
	v_mov_b32_e32 v53, v54
	v_pk_fma_f32 v[70:71], v[2:3], v[70:71], v[10:11]
	v_pk_fma_f32 v[68:69], v[0:1], v[68:69], v[8:9]
	global_store_dwordx4 v[72:73], v[48:51], off nt
	global_store_dwordx4 v[72:73], v[68:71], off offset:16 nt
	v_pk_mul_f32 v[60:61], v[60:61], v[76:77] op_sel_hi:[1,0]
	v_pk_mul_f32 v[48:49], v[62:63], v[76:77] op_sel_hi:[1,0]
	v_pk_mul_f32 v[50:51], v[64:65], v[76:77] op_sel_hi:[1,0]
	v_pk_mul_f32 v[52:53], v[52:53], v[76:77] op_sel_hi:[1,0]
	v_pk_fma_f32 v[50:51], v[18:19], v[50:51], v[22:23]
	v_pk_fma_f32 v[48:49], v[16:17], v[48:49], v[20:21]
	v_pk_fma_f32 v[54:55], v[26:27], v[52:53], v[30:31]
	v_pk_fma_f32 v[52:53], v[24:25], v[60:61], v[28:29]
	global_store_dwordx4 v[72:73], v[48:51], off offset:2048 nt
	global_store_dwordx4 v[72:73], v[52:55], off offset:2064 nt
	s_sub_i32 s0, s5, s4
	v_mov_b64_e32 v[50:51], v[42:43]
	v_mov_b64_e32 v[54:55], v[46:47]
	s_cmp_lt_i32 s0, 0x10200
	v_mov_b64_e32 v[52:53], v[44:45]
	v_mov_b64_e32 v[48:49], v[40:41]
	s_cbranch_scc1 .LBB0_1635
	s_getpc_b64 s[98:99]
